# in-projection column-tile relabelling tn -> (5 tn + 13) mod 22 (offset re-chosen from instruction-count-calibrated epilogue costs)
# speedup vs baseline: 1.0071x; 1.0071x over previous
.LBB0_241:
	s_andn2_b64 vcc, exec, s[0:1]
	s_cbranch_vccnz .LBB0_243
	s_and_b32 s0, s58, 0xffff
	s_mul_i32 s0, s0, 0xba2f
	s_lshr_b32 s0, s0, 23
	s_mul_i32 s1, s0, 0xb0
	s_sub_i32 s1, s58, s1
	s_bfe_u32 s42, s1, 0xd0003
	s_lshl_b32 s0, s0, 3
	s_and_b32 s1, s1, 7
	s_or_b32 s18, s1, s0
	s_mul_i32 s0, s42, 5
	s_add_i32 s0, s0, 13
	s_mul_i32 s1, s0, 0xba3
	s_lshr_b32 s1, s1, 16
	s_mul_i32 s1, s1, 22
	s_sub_i32 s42, s0, s1
